# S5 carry scan parallelised over the 8 waves (32 chunks each from zero state, end states exchanged through spare LDS, a^32 recombination) instead of 256 serial steps on wave 0
# speedup vs baseline: 1.0038x; 1.0038x over previous
; #define LAS __attribute__((address_space(3)))
;     __device__ __forceinline__ void fused(const f32x4 (&acc)[2][2][4][2], const pg8::Unit& u, int wr, int wc, int fr, int fq, LAS unsigned char* lds, int wid, int lane) const {
;     ...
;                 for (int m = 0; m < 4; ++m) { LAS float* tp = T + (ai * 128 + wr * 64 + m * 16 + fr) * TP + wc * 32 + fq * 8;
;                     *(LAS f32x4*)tp = acc[ai][bj][m][0]; *(LAS f32x4*)(tp + 4) = acc[ai][bj][m][1]; }
;             asm volatile("s_waitcnt lgkmcnt(0)" ::: "memory"); __builtin_amdgcn_s_barrier(); asm volatile("" ::: "memory");
;             if (wid == 0) {
;                 const int p = lane, d = bj;
;                 const f32x2 a = AT[((l * NG + g) * 2 + d) * NP + p];
;                 float xr = 0.f, xi = 0.f;
;                 for (int i0 = 0; i0 < 256; i0 += 8) {
;                     float sr[8], si[8];
; #pragma unroll
;                     for (int i = 0; i < 8; ++i) { const int c = d == 0 ? i0 + i : 255 - (i0 + i); sr[i] = T[c * TP + p]; si[i] = T[c * TP + 64 + p]; }
; #pragma unroll
;                     for (int i = 0; i < 8; ++i) { const int c = d == 0 ? i0 + i : 255 - (i0 + i);
;                         T[c * TP + p] = xr; T[c * TP + 64 + p] = xi;
;                         const float nr = a.x * xr - a.y * xi + sr[i]; xi = a.x * xi + a.y * xr + si[i]; xr = nr; }
;                 }
;             }
.LBB0_244:
	v_and_b32_e32 v130, 63, v1
	s_lshl_b32 s0, s46, 7
	v_lshlrev_b32_e32 v1, 1, v1
	s_add_i32 s4, s0, 0
	v_and_b32_e32 v1, 0x60, v1
	v_mul_lo_u32 v131, v142, s54
	v_add3_u32 v131, s4, v1, v131
	s_waitcnt vmcnt(0)
	s_barrier
	ds_write_b128 v131, v[126:129]
	ds_write_b128 v131, v[122:125] offset:16
	ds_write_b128 v131, v[118:121] offset:8448
	ds_write_b128 v131, v[114:117] offset:8464
	ds_write_b128 v131, v[110:113] offset:16896
	ds_write_b128 v131, v[106:109] offset:16912
	ds_write_b128 v131, v[102:105] offset:25344
	ds_write_b128 v131, v[98:101] offset:25360
	v_add_u32_e32 v98, 0x10800, v131
	ds_write_b128 v98, v[94:97]
	v_add_u32_e32 v94, 0x10810, v131
	ds_write_b128 v94, v[90:93]
	v_add_u32_e32 v93, 0x12900, v131
	v_add_u32_e32 v95, 0x12910, v131
	v_add_u32_e32 v96, 0x14a00, v131
	v_add_u32_e32 v97, 0x14a10, v131
	v_add_u32_e32 v99, 0x16b00, v131
	v_add_u32_e32 v100, 0x16b10, v131
	ds_write_b128 v93, v[86:89]
	ds_write_b128 v95, v[82:85]
	ds_write_b128 v96, v[78:81]
	ds_write_b128 v97, v[74:77]
	ds_write_b128 v99, v[70:73]
	ds_write_b128 v100, v[66:69]
	s_waitcnt lgkmcnt(0)
	s_barrier
	s_cmp_lt_u32 s10, 64
	v_or_b32_e32 v82, s75, v130
	s_cselect_b64 s[0:1], -1, 0
	s_cmp_gt_u32 s10, 63
	v_ashrrev_i32_e32 v83, 31, v82
	v_readlane_b32 s4, v252, 34
	v_readlane_b32 s5, v252, 35
	v_lshrrev_b32_e32 v71, 6, v244
	s_nop 1
	v_lshl_add_u64 v[66:67], v[82:83], 3, s[4:5]
	global_load_dwordx2 v[66:67], v[66:67], off
	v_mul_u32_u24_e32 v72, 0x4200, v71
	v_lshl_add_u32 v70, v130, 2, v72
	v_lshl_add_u32 v84, v71, 9, 0
	v_lshl_add_u32 v84, v130, 2, v84
	v_add_u32_e32 v84, 0x21000, v84
	v_mov_b32_e32 v80, v70
	v_mov_b32_e32 v68, 0
	v_mov_b32_e32 v69, 0
	s_mov_b32 s4, 4
	s_waitcnt vmcnt(0)
.Lscan_p1_f:
	ds_read_b32 v85, v70
	ds_read_b32 v86, v70 offset:256
	ds_read_b32 v87, v70 offset:528
	ds_read_b32 v88, v70 offset:784
	ds_read_b32 v89, v70 offset:1056
	ds_read_b32 v90, v70 offset:1312
	ds_read_b32 v91, v70 offset:1584
	ds_read_b32 v92, v70 offset:1840
	ds_read_b32 v101, v70 offset:2112
	ds_read_b32 v102, v70 offset:2368
	ds_read_b32 v103, v70 offset:2640
	ds_read_b32 v104, v70 offset:2896
	ds_read_b32 v105, v70 offset:3168
	ds_read_b32 v106, v70 offset:3424
	ds_read_b32 v107, v70 offset:3696
	ds_read_b32 v108, v70 offset:3952
	s_waitcnt lgkmcnt(0)
	ds_write_b32 v70, v68
	ds_write_b32 v70, v69 offset:256
	v_fma_f32 v72, v66, v68, v85
	v_fma_f32 v73, v66, v69, v86
	v_fma_f32 v72, -v67, v69, v72
	v_fma_f32 v69, v67, v68, v73
	v_mov_b32_e32 v68, v72
	ds_write_b32 v70, v68 offset:528
	ds_write_b32 v70, v69 offset:784
	v_fma_f32 v72, v66, v68, v87
	v_fma_f32 v73, v66, v69, v88
	v_fma_f32 v72, -v67, v69, v72
	v_fma_f32 v69, v67, v68, v73
	v_mov_b32_e32 v68, v72
	ds_write_b32 v70, v68 offset:1056
	ds_write_b32 v70, v69 offset:1312
	v_fma_f32 v72, v66, v68, v89
	v_fma_f32 v73, v66, v69, v90
	v_fma_f32 v72, -v67, v69, v72
	v_fma_f32 v69, v67, v68, v73
	v_mov_b32_e32 v68, v72
	ds_write_b32 v70, v68 offset:1584
	ds_write_b32 v70, v69 offset:1840
	v_fma_f32 v72, v66, v68, v91
	v_fma_f32 v73, v66, v69, v92
	v_fma_f32 v72, -v67, v69, v72
	v_fma_f32 v69, v67, v68, v73
	v_mov_b32_e32 v68, v72
	ds_write_b32 v70, v68 offset:2112
	ds_write_b32 v70, v69 offset:2368
	v_fma_f32 v72, v66, v68, v101
	v_fma_f32 v73, v66, v69, v102
	v_fma_f32 v72, -v67, v69, v72
	v_fma_f32 v69, v67, v68, v73
	v_mov_b32_e32 v68, v72
	ds_write_b32 v70, v68 offset:2640
	ds_write_b32 v70, v69 offset:2896
	v_fma_f32 v72, v66, v68, v103
	v_fma_f32 v73, v66, v69, v104
	v_fma_f32 v72, -v67, v69, v72
	v_fma_f32 v69, v67, v68, v73
	v_mov_b32_e32 v68, v72
	ds_write_b32 v70, v68 offset:3168
	ds_write_b32 v70, v69 offset:3424
	v_fma_f32 v72, v66, v68, v105
	v_fma_f32 v73, v66, v69, v106
	v_fma_f32 v72, -v67, v69, v72
	v_fma_f32 v69, v67, v68, v73
	v_mov_b32_e32 v68, v72
	ds_write_b32 v70, v68 offset:3696
	ds_write_b32 v70, v69 offset:3952
	v_fma_f32 v72, v66, v68, v107
	v_fma_f32 v73, v66, v69, v108
	v_fma_f32 v72, -v67, v69, v72
	v_fma_f32 v69, v67, v68, v73
	v_mov_b32_e32 v68, v72
	v_add_u32_e32 v70, 0x1080, v70
	s_sub_i32 s4, s4, 1
	s_cmp_lg_u32 s4, 0
	s_cbranch_scc1 .Lscan_p1_f
	ds_write_b32 v84, v68
	ds_write_b32 v84, v69 offset:256
	s_waitcnt lgkmcnt(0)
	s_barrier
	s_lshr_b32 s5, s10, 6
	s_cmp_eq_u32 s5, 0
	s_cbranch_scc1 .Lscan_end_f
	v_mov_b32_e32 v74, v66
	v_mov_b32_e32 v75, v67
	v_mul_f32_e32 v72, v74, v74
	v_mul_f32_e32 v73, v74, v75
	v_fma_f32 v74, -v75, v75, v72
	v_add_f32_e32 v75, v73, v73
	v_mul_f32_e32 v72, v74, v74
	v_mul_f32_e32 v73, v74, v75
	v_fma_f32 v74, -v75, v75, v72
	v_add_f32_e32 v75, v73, v73
	v_mul_f32_e32 v72, v74, v74
	v_mul_f32_e32 v73, v74, v75
	v_fma_f32 v74, -v75, v75, v72
	v_add_f32_e32 v75, v73, v73
	v_mul_f32_e32 v72, v74, v74
	v_mul_f32_e32 v73, v74, v75
	v_fma_f32 v74, -v75, v75, v72
	v_add_f32_e32 v75, v73, v73
	v_mul_f32_e32 v72, v74, v74
	v_mul_f32_e32 v73, v74, v75
	v_fma_f32 v74, -v75, v75, v72
	v_add_f32_e32 v75, v73, v73
	v_mov_b32_e32 v76, 0
	v_mov_b32_e32 v77, 0
	v_lshl_add_u32 v84, v130, 2, 0
	v_add_u32_e32 v84, 0x21000, v84
.Lscan_x_f:
	ds_read_b32 v72, v84
	ds_read_b32 v73, v84 offset:256
	v_add_u32_e32 v84, 0x200, v84
	s_waitcnt lgkmcnt(0)
	v_fma_f32 v72, v74, v76, v72
	v_fma_f32 v73, v74, v77, v73
	v_fma_f32 v72, -v75, v77, v72
	v_fma_f32 v77, v75, v76, v73
	v_mov_b32_e32 v76, v72
	s_sub_i32 s5, s5, 1
	s_cmp_lg_u32 s5, 0
	s_cbranch_scc1 .Lscan_x_f
	v_mov_b32_e32 v78, 1.0
	v_mov_b32_e32 v79, 0
	v_mov_b32_e32 v70, v80
	s_mov_b32 s4, 4
; __device__ __forceinline__ unsigned cvt_pk_bf16(float lo, float hi) { unsigned r; asm volatile("v_cvt_pk_bf16_f32 %0, %1, %2" : "=v"(r) : "v"(lo), "v"(hi)); return r; }
; #define LAS __attribute__((address_space(3)))
;     __device__ __forceinline__ void fused(const f32x4 (&acc)[2][2][4][2], const pg8::Unit& u, int wr, int wc, int fr, int fq, LAS unsigned char* lds, int wid, int lane) const {
;     ...
;             if (wid == 0) {
;                 const int p = lane, d = bj;
;                 const f32x2 a = AT[((l * NG + g) * 2 + d) * NP + p];
;                 float xr = 0.f, xi = 0.f;
;                 for (int i0 = 0; i0 < 256; i0 += 8) {
;                     float sr[8], si[8];
; #pragma unroll
;                     for (int i = 0; i < 8; ++i) { const int c = d == 0 ? i0 + i : 255 - (i0 + i); sr[i] = T[c * TP + p]; si[i] = T[c * TP + 64 + p]; }
; #pragma unroll
;                     for (int i = 0; i < 8; ++i) { const int c = d == 0 ? i0 + i : 255 - (i0 + i);
;                         T[c * TP + p] = xr; T[c * TP + 64 + p] = xi;
;                         const float nr = a.x * xr - a.y * xi + sr[i]; xi = a.x * xi + a.y * xr + si[i]; xr = nr; }
;                 }
;             }
;             asm volatile("s_waitcnt lgkmcnt(0)" ::: "memory"); __builtin_amdgcn_s_barrier(); asm volatile("" ::: "memory");
;             {
;                 const int tid = wid * 64 + lane;
; #pragma unroll
;                 for (int q = 0; q < 8; ++q) { const int e = q * 512 + tid, c = e >> 4, k8 = (e & 15) * 8;
;                     const f32x4 v0 = *(const LAS f32x4*)(T + c * TP + k8), v1 = *(const LAS f32x4*)(T + c * TP + k8 + 4);
;                     v4u w; w.x = cvt_pk_bf16(v0[0], v0[1]); w.y = cvt_pk_bf16(v0[2], v0[3]); w.z = cvt_pk_bf16(v1[0], v1[1]); w.w = cvt_pk_bf16(v1[2], v1[3]);
;                     *(v4u*)(A2 + (row0 + c) * K2 + 512 + bj * 128 + k8) = w; }
.Lscan_p2_f:
	ds_read_b32 v85, v70
	ds_read_b32 v86, v70 offset:256
	ds_read_b32 v87, v70 offset:528
	ds_read_b32 v88, v70 offset:784
	ds_read_b32 v89, v70 offset:1056
	ds_read_b32 v90, v70 offset:1312
	ds_read_b32 v91, v70 offset:1584
	ds_read_b32 v92, v70 offset:1840
	ds_read_b32 v101, v70 offset:2112
	ds_read_b32 v102, v70 offset:2368
	ds_read_b32 v103, v70 offset:2640
	ds_read_b32 v104, v70 offset:2896
	ds_read_b32 v105, v70 offset:3168
	ds_read_b32 v106, v70 offset:3424
	ds_read_b32 v107, v70 offset:3696
	ds_read_b32 v108, v70 offset:3952
	s_waitcnt lgkmcnt(0)
	v_fma_f32 v85, v78, v76, v85
	v_fma_f32 v86, v78, v77, v86
	v_fma_f32 v85, -v79, v77, v85
	v_fma_f32 v86, v79, v76, v86
	ds_write_b32 v70, v85
	ds_write_b32 v70, v86 offset:256
	v_mul_f32_e32 v72, v78, v66
	v_mul_f32_e32 v73, v78, v67
	v_fma_f32 v78, -v79, v67, v72
	v_fma_f32 v79, v79, v66, v73
	v_fma_f32 v87, v78, v76, v87
	v_fma_f32 v88, v78, v77, v88
	v_fma_f32 v87, -v79, v77, v87
	v_fma_f32 v88, v79, v76, v88
	ds_write_b32 v70, v87 offset:528
	ds_write_b32 v70, v88 offset:784
	v_mul_f32_e32 v72, v78, v66
	v_mul_f32_e32 v73, v78, v67
	v_fma_f32 v78, -v79, v67, v72
	v_fma_f32 v79, v79, v66, v73
	v_fma_f32 v89, v78, v76, v89
	v_fma_f32 v90, v78, v77, v90
	v_fma_f32 v89, -v79, v77, v89
	v_fma_f32 v90, v79, v76, v90
	ds_write_b32 v70, v89 offset:1056
	ds_write_b32 v70, v90 offset:1312
	v_mul_f32_e32 v72, v78, v66
	v_mul_f32_e32 v73, v78, v67
	v_fma_f32 v78, -v79, v67, v72
	v_fma_f32 v79, v79, v66, v73
	v_fma_f32 v91, v78, v76, v91
	v_fma_f32 v92, v78, v77, v92
	v_fma_f32 v91, -v79, v77, v91
	v_fma_f32 v92, v79, v76, v92
	ds_write_b32 v70, v91 offset:1584
	ds_write_b32 v70, v92 offset:1840
	v_mul_f32_e32 v72, v78, v66
	v_mul_f32_e32 v73, v78, v67
	v_fma_f32 v78, -v79, v67, v72
	v_fma_f32 v79, v79, v66, v73
	v_fma_f32 v101, v78, v76, v101
	v_fma_f32 v102, v78, v77, v102
	v_fma_f32 v101, -v79, v77, v101
	v_fma_f32 v102, v79, v76, v102
	ds_write_b32 v70, v101 offset:2112
	ds_write_b32 v70, v102 offset:2368
	v_mul_f32_e32 v72, v78, v66
	v_mul_f32_e32 v73, v78, v67
	v_fma_f32 v78, -v79, v67, v72
	v_fma_f32 v79, v79, v66, v73
	v_fma_f32 v103, v78, v76, v103
	v_fma_f32 v104, v78, v77, v104
	v_fma_f32 v103, -v79, v77, v103
	v_fma_f32 v104, v79, v76, v104
	ds_write_b32 v70, v103 offset:2640
	ds_write_b32 v70, v104 offset:2896
	v_mul_f32_e32 v72, v78, v66
	v_mul_f32_e32 v73, v78, v67
	v_fma_f32 v78, -v79, v67, v72
	v_fma_f32 v79, v79, v66, v73
	v_fma_f32 v105, v78, v76, v105
	v_fma_f32 v106, v78, v77, v106
	v_fma_f32 v105, -v79, v77, v105
	v_fma_f32 v106, v79, v76, v106
	ds_write_b32 v70, v105 offset:3168
	ds_write_b32 v70, v106 offset:3424
	v_mul_f32_e32 v72, v78, v66
	v_mul_f32_e32 v73, v78, v67
	v_fma_f32 v78, -v79, v67, v72
	v_fma_f32 v79, v79, v66, v73
	v_fma_f32 v107, v78, v76, v107
	v_fma_f32 v108, v78, v77, v108
	v_fma_f32 v107, -v79, v77, v107
	v_fma_f32 v108, v79, v76, v108
	ds_write_b32 v70, v107 offset:3696
	ds_write_b32 v70, v108 offset:3952
	v_mul_f32_e32 v72, v78, v66
	v_mul_f32_e32 v73, v78, v67
	v_fma_f32 v78, -v79, v67, v72
	v_fma_f32 v79, v79, v66, v73
	v_add_u32_e32 v70, 0x1080, v70
	s_sub_i32 s4, s4, 1
	s_cmp_lg_u32 s4, 0
	s_cbranch_scc1 .Lscan_p2_f
.Lscan_end_f:
.LBB0_247:
	s_andn2_b32 s10, s10, 63
	v_or_b32_e32 v92, s10, v130
	v_lshlrev_b32_e32 v1, 3, v130
	v_and_b32_e32 v84, 0x78, v1
	v_ashrrev_i32_e32 v78, 4, v92
	v_lshl_add_u32 v101, v84, 2, 0
	v_mul_lo_u32 v1, v78, s54
	s_waitcnt lgkmcnt(0)
	s_barrier
	v_add_u32_e32 v1, v101, v1
	ds_read_b128 v[66:69], v1
	ds_read_b128 v[70:73], v1 offset:16
	v_readlane_b32 s4, v253, 19
	v_ashrrev_i32_e32 v79, 31, v78
	v_readlane_b32 s5, v253, 20
	s_waitcnt lgkmcnt(0)
	v_cvt_pk_bf16_f32 v74, v66, v67
	v_lshl_add_u64 v[66:67], s[38:39], 0, v[78:79]
	v_cvt_pk_bf16_f32 v75, v68, v69
	v_lshlrev_b32_e32 v84, 1, v84
	v_mov_b64_e32 v[80:81], s[4:5]
	v_mad_u64_u32 v[68:69], s[4:5], v66, s89, v[80:81]
	v_mad_i32_i24 v69, v67, s89, v69
	v_mov_b32_e32 v85, v0
	v_lshl_add_u64 v[66:67], v[68:69], 0, v[84:85]
	v_add_u32_e32 v68, 0x200, v92
	v_ashrrev_i32_e32 v88, 4, v68
	v_mul_lo_u32 v68, v88, s54
	v_cvt_pk_bf16_f32 v76, v70, v71
	v_cvt_pk_bf16_f32 v77, v72, v73
	global_store_dwordx4 v[66:67], v[74:77], off offset:1024
	v_add_u32_e32 v86, v101, v68
	ds_read_b128 v[68:71], v86
	ds_read_b128 v[72:75], v86 offset:16
	v_ashrrev_i32_e32 v89, 31, v88
	s_waitcnt lgkmcnt(0)
	v_cvt_pk_bf16_f32 v76, v68, v69
	v_lshl_add_u64 v[68:69], s[38:39], 0, v[88:89]
	v_cvt_pk_bf16_f32 v77, v70, v71
	v_mad_u64_u32 v[70:71], s[4:5], v68, s89, v[80:81]
	v_mad_i32_i24 v71, v69, s89, v71
	v_cvt_pk_bf16_f32 v78, v72, v73
	v_lshl_add_u64 v[68:69], v[70:71], 0, v[84:85]
	v_add_u32_e32 v70, 0x400, v92
	v_cvt_pk_bf16_f32 v79, v74, v75
	global_store_dwordx4 v[68:69], v[76:79], off offset:1024
	s_andn2_b64 vcc, exec, s[0:1]
	s_nop 0
	v_ashrrev_i32_e32 v78, 4, v70
	v_mul_lo_u32 v70, v78, s54
	v_add_u32_e32 v87, v101, v70
	ds_read_b128 v[70:73], v87
	ds_read_b128 v[74:77], v87 offset:16
	v_ashrrev_i32_e32 v79, 31, v78
	s_waitcnt lgkmcnt(0)
	v_cvt_pk_bf16_f32 v88, v70, v71
	v_lshl_add_u64 v[70:71], s[38:39], 0, v[78:79]
	v_cvt_pk_bf16_f32 v89, v72, v73
	v_mad_u64_u32 v[72:73], s[4:5], v70, s89, v[80:81]
	v_mad_i32_i24 v73, v71, s89, v73
	v_cvt_pk_bf16_f32 v90, v74, v75
	v_lshl_add_u64 v[70:71], v[72:73], 0, v[84:85]
	v_add_u32_e32 v72, 0x600, v92
	v_cvt_pk_bf16_f32 v91, v76, v77
	global_store_dwordx4 v[70:71], v[88:91], off offset:1024
	s_nop 1
	v_ashrrev_i32_e32 v90, 4, v72
	v_mul_lo_u32 v72, v90, s54
	v_add_u32_e32 v88, v101, v72
	ds_read_b128 v[72:75], v88
	ds_read_b128 v[76:79], v88 offset:16
	v_ashrrev_i32_e32 v91, 31, v90
	s_waitcnt lgkmcnt(0)
; __device__ __forceinline__ unsigned cvt_pk_bf16(float lo, float hi) { unsigned r; asm volatile("v_cvt_pk_bf16_f32 %0, %1, %2" : "=v"(r) : "v"(lo), "v"(hi)); return r; }
; #define LAS __attribute__((address_space(3)))
;     __device__ __forceinline__ void fused(const f32x4 (&acc)[2][2][4][2], const pg8::Unit& u, int wr, int wc, int fr, int fq, LAS unsigned char* lds, int wid, int lane) const {
;     ...
;                 for (int m = 0; m < 4; ++m) { LAS float* tp = T + (ai * 128 + wr * 64 + m * 16 + fr) * TP + wc * 32 + fq * 8;
;                     *(LAS f32x4*)tp = acc[ai][bj][m][0]; *(LAS f32x4*)(tp + 4) = acc[ai][bj][m][1]; }
;             asm volatile("s_waitcnt lgkmcnt(0)" ::: "memory"); __builtin_amdgcn_s_barrier(); asm volatile("" ::: "memory");
;             if (wid == 0) {
;                 const int p = lane, d = bj;
;                 const f32x2 a = AT[((l * NG + g) * 2 + d) * NP + p];
;                 float xr = 0.f, xi = 0.f;
;                 for (int i0 = 0; i0 < 256; i0 += 8) {
;                     float sr[8], si[8];
; #pragma unroll
;                     for (int i = 0; i < 8; ++i) { const int c = d == 0 ? i0 + i : 255 - (i0 + i); sr[i] = T[c * TP + p]; si[i] = T[c * TP + 64 + p]; }
; #pragma unroll
;                     for (int i = 0; i < 8; ++i) { const int c = d == 0 ? i0 + i : 255 - (i0 + i);
;                         T[c * TP + p] = xr; T[c * TP + 64 + p] = xi;
;                         const float nr = a.x * xr - a.y * xi + sr[i]; xi = a.x * xi + a.y * xr + si[i]; xr = nr; }
;                 }
;             }
;             asm volatile("s_waitcnt lgkmcnt(0)" ::: "memory"); __builtin_amdgcn_s_barrier(); asm volatile("" ::: "memory");
;             {
;                 const int tid = wid * 64 + lane;
; #pragma unroll
;                 for (int q = 0; q < 8; ++q) { const int e = q * 512 + tid, c = e >> 4, k8 = (e & 15) * 8;
;                     const f32x4 v0 = *(const LAS f32x4*)(T + c * TP + k8), v1 = *(const LAS f32x4*)(T + c * TP + k8 + 4);
;                     v4u w; w.x = cvt_pk_bf16(v0[0], v0[1]); w.y = cvt_pk_bf16(v0[2], v0[3]); w.z = cvt_pk_bf16(v1[0], v1[1]); w.w = cvt_pk_bf16(v1[2], v1[3]);
;                     *(v4u*)(A2 + (row0 + c) * K2 + 512 + bj * 128 + k8) = w; }
	v_cvt_pk_bf16_f32 v102, v72, v73
	v_lshl_add_u64 v[72:73], s[38:39], 0, v[90:91]
	v_cvt_pk_bf16_f32 v103, v74, v75
	v_mad_u64_u32 v[74:75], s[4:5], v72, s89, v[80:81]
	v_mad_i32_i24 v75, v73, s89, v75
	v_lshl_add_u64 v[72:73], v[74:75], 0, v[84:85]
	v_add_u32_e32 v74, 0x800, v92
	v_cvt_pk_bf16_f32 v104, v76, v77
	v_cvt_pk_bf16_f32 v105, v78, v79
	v_ashrrev_i32_e32 v78, 4, v74
	v_mul_lo_u32 v74, v78, s54
	global_store_dwordx4 v[72:73], v[102:105], off offset:1024
	v_add_u32_e32 v89, v101, v74
	ds_read_b128 v[74:77], v89
	ds_read_b128 v[102:105], v89 offset:16
	v_ashrrev_i32_e32 v79, 31, v78
	s_waitcnt lgkmcnt(0)
	v_cvt_pk_bf16_f32 v106, v74, v75
	v_lshl_add_u64 v[74:75], s[38:39], 0, v[78:79]
	v_cvt_pk_bf16_f32 v107, v76, v77
	v_mad_u64_u32 v[76:77], s[4:5], v74, s89, v[80:81]
	v_mad_i32_i24 v77, v75, s89, v77
	v_lshl_add_u64 v[74:75], v[76:77], 0, v[84:85]
	v_add_u32_e32 v76, 0xa00, v92
	v_ashrrev_i32_e32 v110, 4, v76
	v_mul_lo_u32 v76, v110, s54
	v_cvt_pk_bf16_f32 v108, v102, v103
	v_cvt_pk_bf16_f32 v109, v104, v105
	global_store_dwordx4 v[74:75], v[106:109], off offset:1024
	v_add_u32_e32 v90, v101, v76
	ds_read_b128 v[76:79], v90
	ds_read_b128 v[102:105], v90 offset:16
	v_ashrrev_i32_e32 v111, 31, v110
	s_waitcnt lgkmcnt(0)
	v_cvt_pk_bf16_f32 v106, v76, v77
	v_lshl_add_u64 v[76:77], s[38:39], 0, v[110:111]
	v_cvt_pk_bf16_f32 v107, v78, v79
	v_mad_u64_u32 v[78:79], s[4:5], v76, s89, v[80:81]
	v_mad_i32_i24 v79, v77, s89, v79
	v_lshl_add_u64 v[76:77], v[78:79], 0, v[84:85]
	v_add_u32_e32 v78, 0xc00, v92
	v_ashrrev_i32_e32 v78, 4, v78
	v_mul_lo_u32 v79, v78, s54
	v_cvt_pk_bf16_f32 v108, v102, v103
	v_cvt_pk_bf16_f32 v109, v104, v105
	global_store_dwordx4 v[76:77], v[106:109], off offset:1024
	v_add_u32_e32 v91, v101, v79
	ds_read_b128 v[102:105], v91
	ds_read_b128 v[106:109], v91 offset:16
	v_ashrrev_i32_e32 v79, 31, v78
	v_lshl_add_u64 v[78:79], s[38:39], 0, v[78:79]
	s_waitcnt lgkmcnt(0)
	v_cvt_pk_bf16_f32 v102, v102, v103
	v_cvt_pk_bf16_f32 v103, v104, v105
	v_cvt_pk_bf16_f32 v104, v106, v107
	v_mad_u64_u32 v[106:107], s[4:5], v78, s89, v[80:81]
	v_add_u32_e32 v92, 0xe00, v92
	v_mad_i32_i24 v107, v79, s89, v107
	v_ashrrev_i32_e32 v110, 4, v92
	v_lshl_add_u64 v[78:79], v[106:107], 0, v[84:85]
	v_mul_lo_u32 v92, v110, s54
	v_cvt_pk_bf16_f32 v105, v108, v109
	global_store_dwordx4 v[78:79], v[102:105], off offset:1024
	v_add_u32_e32 v92, v101, v92
	ds_read_b128 v[102:105], v92
	ds_read_b128 v[106:109], v92 offset:16
	v_ashrrev_i32_e32 v111, 31, v110
	s_waitcnt lgkmcnt(0)
	v_cvt_pk_bf16_f32 v102, v102, v103
	v_cvt_pk_bf16_f32 v103, v104, v105
	v_cvt_pk_bf16_f32 v104, v106, v107
	v_lshl_add_u64 v[106:107], s[38:39], 0, v[110:111]
	v_mad_u64_u32 v[80:81], s[4:5], v106, s89, v[80:81]
	v_mad_i32_i24 v81, v107, s89, v81
	v_lshl_add_u64 v[80:81], v[80:81], 0, v[84:85]
	v_cvt_pk_bf16_f32 v105, v108, v109
	global_store_dwordx4 v[80:81], v[102:105], off offset:1024
	s_waitcnt vmcnt(0) lgkmcnt(0)
	s_barrier
	ds_write_b128 v131, v[62:65]
	ds_write_b128 v131, v[58:61] offset:16
	ds_write_b128 v131, v[54:57] offset:8448
	ds_write_b128 v131, v[50:53] offset:8464
	ds_write_b128 v131, v[46:49] offset:16896
	ds_write_b128 v131, v[42:45] offset:16912
	ds_write_b128 v131, v[38:41] offset:25344
	ds_write_b128 v131, v[34:37] offset:25360
	ds_write_b128 v98, v[30:33]
	ds_write_b128 v94, v[26:29]
	ds_write_b128 v93, v[22:25]
	ds_write_b128 v95, v[18:21]
	ds_write_b128 v96, v[14:17]
	ds_write_b128 v97, v[10:13]
	ds_write_b128 v99, v[6:9]
	ds_write_b128 v100, v[2:5]
	s_waitcnt lgkmcnt(0)
	s_barrier
	v_readlane_b32 s0, v252, 34
	v_readlane_b32 s1, v252, 35
	v_lshrrev_b32_e32 v7, 6, v244
	s_nop 1
	v_lshl_add_u64 v[2:3], v[82:83], 3, s[0:1]
	global_load_dwordx2 v[2:3], v[2:3], off offset:512
	v_mul_u32_u24_e32 v8, 0x4200, v7
	v_lshlrev_b32_e32 v9, 2, v130
	v_sub_u32_e32 v6, v9, v8
	v_add_u32_e32 v6, 0x1ff80, v6
	v_lshl_add_u32 v18, v7, 9, 0
	v_lshl_add_u32 v18, v130, 2, v18
	v_add_u32_e32 v18, 0x21000, v18
	v_mov_b32_e32 v16, v6
	v_mov_b32_e32 v4, 0
	v_mov_b32_e32 v5, 0
	s_mov_b32 s0, 4
	s_waitcnt vmcnt(0)
.Lscan_p1_b:
	ds_read_b32 v19, v6 offset:3696
	ds_read_b32 v20, v6 offset:3952
	ds_read_b32 v21, v6 offset:3168
	ds_read_b32 v22, v6 offset:3424
	ds_read_b32 v23, v6 offset:2640
	ds_read_b32 v24, v6 offset:2896
	ds_read_b32 v25, v6 offset:2112
	ds_read_b32 v26, v6 offset:2368
	ds_read_b32 v27, v6 offset:1584
	ds_read_b32 v28, v6 offset:1840
	ds_read_b32 v29, v6 offset:1056
	ds_read_b32 v30, v6 offset:1312
	ds_read_b32 v31, v6 offset:528
	ds_read_b32 v32, v6 offset:784
	ds_read_b32 v33, v6
	ds_read_b32 v34, v6 offset:256
	s_waitcnt lgkmcnt(0)
	ds_write_b32 v6, v4 offset:3696
	ds_write_b32 v6, v5 offset:3952
	v_fma_f32 v8, v2, v4, v19
	v_fma_f32 v9, v2, v5, v20
	v_fma_f32 v8, -v3, v5, v8
	v_fma_f32 v5, v3, v4, v9
	v_mov_b32_e32 v4, v8
	ds_write_b32 v6, v4 offset:3168
	ds_write_b32 v6, v5 offset:3424
	v_fma_f32 v8, v2, v4, v21
	v_fma_f32 v9, v2, v5, v22
	v_fma_f32 v8, -v3, v5, v8
	v_fma_f32 v5, v3, v4, v9
	v_mov_b32_e32 v4, v8
	ds_write_b32 v6, v4 offset:2640
	ds_write_b32 v6, v5 offset:2896
	v_fma_f32 v8, v2, v4, v23
	v_fma_f32 v9, v2, v5, v24
	v_fma_f32 v8, -v3, v5, v8
	v_fma_f32 v5, v3, v4, v9
	v_mov_b32_e32 v4, v8
	ds_write_b32 v6, v4 offset:2112
	ds_write_b32 v6, v5 offset:2368
	v_fma_f32 v8, v2, v4, v25
	v_fma_f32 v9, v2, v5, v26
	v_fma_f32 v8, -v3, v5, v8
	v_fma_f32 v5, v3, v4, v9
	v_mov_b32_e32 v4, v8
	ds_write_b32 v6, v4 offset:1584
	ds_write_b32 v6, v5 offset:1840
	v_fma_f32 v8, v2, v4, v27
	v_fma_f32 v9, v2, v5, v28
	v_fma_f32 v8, -v3, v5, v8
	v_fma_f32 v5, v3, v4, v9
	v_mov_b32_e32 v4, v8
	ds_write_b32 v6, v4 offset:1056
	ds_write_b32 v6, v5 offset:1312
	v_fma_f32 v8, v2, v4, v29
	v_fma_f32 v9, v2, v5, v30
	v_fma_f32 v8, -v3, v5, v8
	v_fma_f32 v5, v3, v4, v9
	v_mov_b32_e32 v4, v8
	ds_write_b32 v6, v4 offset:528
	ds_write_b32 v6, v5 offset:784
	v_fma_f32 v8, v2, v4, v31
	v_fma_f32 v9, v2, v5, v32
	v_fma_f32 v8, -v3, v5, v8
	v_fma_f32 v5, v3, v4, v9
	v_mov_b32_e32 v4, v8
	ds_write_b32 v6, v4
	ds_write_b32 v6, v5 offset:256
	v_fma_f32 v8, v2, v4, v33
	v_fma_f32 v9, v2, v5, v34
	v_fma_f32 v8, -v3, v5, v8
	v_fma_f32 v5, v3, v4, v9
	v_mov_b32_e32 v4, v8
	v_add_u32_e32 v6, 0xffffef80, v6
	s_sub_i32 s0, s0, 1
	s_cmp_lg_u32 s0, 0
	s_cbranch_scc1 .Lscan_p1_b
;     __device__ __forceinline__ void fused(const f32x4 (&acc)[2][2][4][2], const pg8::Unit& u, int wr, int wc, int fr, int fq, LAS unsigned char* lds, int wid, int lane) const {
;     ...
;             if (wid == 0) {
;                 const int p = lane, d = bj;
;                 const f32x2 a = AT[((l * NG + g) * 2 + d) * NP + p];
;                 float xr = 0.f, xi = 0.f;
;                 for (int i0 = 0; i0 < 256; i0 += 8) {
;                     float sr[8], si[8];
; #pragma unroll
;                     for (int i = 0; i < 8; ++i) { const int c = d == 0 ? i0 + i : 255 - (i0 + i); sr[i] = T[c * TP + p]; si[i] = T[c * TP + 64 + p]; }
; #pragma unroll
;                     for (int i = 0; i < 8; ++i) { const int c = d == 0 ? i0 + i : 255 - (i0 + i);
;                         T[c * TP + p] = xr; T[c * TP + 64 + p] = xi;
;                         const float nr = a.x * xr - a.y * xi + sr[i]; xi = a.x * xi + a.y * xr + si[i]; xr = nr; }
;                 }
;             }
	ds_write_b32 v18, v4
	ds_write_b32 v18, v5 offset:256
	s_waitcnt lgkmcnt(0)
	s_barrier
	s_lshr_b32 s1, s10, 6
	s_cmp_eq_u32 s1, 0
	s_cbranch_scc1 .Lscan_end_b
	v_mov_b32_e32 v10, v2
	v_mov_b32_e32 v11, v3
	v_mul_f32_e32 v8, v10, v10
	v_mul_f32_e32 v9, v10, v11
	v_fma_f32 v10, -v11, v11, v8
	v_add_f32_e32 v11, v9, v9
	v_mul_f32_e32 v8, v10, v10
	v_mul_f32_e32 v9, v10, v11
	v_fma_f32 v10, -v11, v11, v8
	v_add_f32_e32 v11, v9, v9
	v_mul_f32_e32 v8, v10, v10
	v_mul_f32_e32 v9, v10, v11
	v_fma_f32 v10, -v11, v11, v8
	v_add_f32_e32 v11, v9, v9
	v_mul_f32_e32 v8, v10, v10
	v_mul_f32_e32 v9, v10, v11
	v_fma_f32 v10, -v11, v11, v8
	v_add_f32_e32 v11, v9, v9
	v_mul_f32_e32 v8, v10, v10
	v_mul_f32_e32 v9, v10, v11
	v_fma_f32 v10, -v11, v11, v8
	v_add_f32_e32 v11, v9, v9
	v_mov_b32_e32 v12, 0
	v_mov_b32_e32 v13, 0
	v_lshl_add_u32 v18, v130, 2, 0
	v_add_u32_e32 v18, 0x21000, v18
.Lscan_x_b:
	ds_read_b32 v8, v18
	ds_read_b32 v9, v18 offset:256
	v_add_u32_e32 v18, 0x200, v18
	s_waitcnt lgkmcnt(0)
	v_fma_f32 v8, v10, v12, v8
	v_fma_f32 v9, v10, v13, v9
	v_fma_f32 v8, -v11, v13, v8
	v_fma_f32 v13, v11, v12, v9
	v_mov_b32_e32 v12, v8
	s_sub_i32 s1, s1, 1
	s_cmp_lg_u32 s1, 0
	s_cbranch_scc1 .Lscan_x_b
	v_mov_b32_e32 v14, 1.0
	v_mov_b32_e32 v15, 0
	v_mov_b32_e32 v6, v16
	s_mov_b32 s0, 4
.Lscan_p2_b:
	ds_read_b32 v19, v6 offset:3696
	ds_read_b32 v20, v6 offset:3952
	ds_read_b32 v21, v6 offset:3168
	ds_read_b32 v22, v6 offset:3424
	ds_read_b32 v23, v6 offset:2640
	ds_read_b32 v24, v6 offset:2896
	ds_read_b32 v25, v6 offset:2112
	ds_read_b32 v26, v6 offset:2368
	ds_read_b32 v27, v6 offset:1584
	ds_read_b32 v28, v6 offset:1840
	ds_read_b32 v29, v6 offset:1056
	ds_read_b32 v30, v6 offset:1312
	ds_read_b32 v31, v6 offset:528
	ds_read_b32 v32, v6 offset:784
	ds_read_b32 v33, v6
	ds_read_b32 v34, v6 offset:256
	s_waitcnt lgkmcnt(0)
	v_fma_f32 v19, v14, v12, v19
	v_fma_f32 v20, v14, v13, v20
	v_fma_f32 v19, -v15, v13, v19
	v_fma_f32 v20, v15, v12, v20
	ds_write_b32 v6, v19 offset:3696
	ds_write_b32 v6, v20 offset:3952
	v_mul_f32_e32 v8, v14, v2
	v_mul_f32_e32 v9, v14, v3
	v_fma_f32 v14, -v15, v3, v8
	v_fma_f32 v15, v15, v2, v9
	v_fma_f32 v21, v14, v12, v21
	v_fma_f32 v22, v14, v13, v22
	v_fma_f32 v21, -v15, v13, v21
	v_fma_f32 v22, v15, v12, v22
	ds_write_b32 v6, v21 offset:3168
	ds_write_b32 v6, v22 offset:3424
	v_mul_f32_e32 v8, v14, v2
	v_mul_f32_e32 v9, v14, v3
	v_fma_f32 v14, -v15, v3, v8
	v_fma_f32 v15, v15, v2, v9
	v_fma_f32 v23, v14, v12, v23
	v_fma_f32 v24, v14, v13, v24
	v_fma_f32 v23, -v15, v13, v23
	v_fma_f32 v24, v15, v12, v24
	ds_write_b32 v6, v23 offset:2640
	ds_write_b32 v6, v24 offset:2896
	v_mul_f32_e32 v8, v14, v2
	v_mul_f32_e32 v9, v14, v3
	v_fma_f32 v14, -v15, v3, v8
	v_fma_f32 v15, v15, v2, v9
	v_fma_f32 v25, v14, v12, v25
	v_fma_f32 v26, v14, v13, v26
	v_fma_f32 v25, -v15, v13, v25
	v_fma_f32 v26, v15, v12, v26
	ds_write_b32 v6, v25 offset:2112
	ds_write_b32 v6, v26 offset:2368
	v_mul_f32_e32 v8, v14, v2
	v_mul_f32_e32 v9, v14, v3
	v_fma_f32 v14, -v15, v3, v8
	v_fma_f32 v15, v15, v2, v9
	v_fma_f32 v27, v14, v12, v27
	v_fma_f32 v28, v14, v13, v28
	v_fma_f32 v27, -v15, v13, v27
	v_fma_f32 v28, v15, v12, v28
	ds_write_b32 v6, v27 offset:1584
	ds_write_b32 v6, v28 offset:1840
	v_mul_f32_e32 v8, v14, v2
	v_mul_f32_e32 v9, v14, v3
	v_fma_f32 v14, -v15, v3, v8
	v_fma_f32 v15, v15, v2, v9
	v_fma_f32 v29, v14, v12, v29
	v_fma_f32 v30, v14, v13, v30
	v_fma_f32 v29, -v15, v13, v29
	v_fma_f32 v30, v15, v12, v30
	ds_write_b32 v6, v29 offset:1056
	ds_write_b32 v6, v30 offset:1312
	v_mul_f32_e32 v8, v14, v2
	v_mul_f32_e32 v9, v14, v3
	v_fma_f32 v14, -v15, v3, v8
	v_fma_f32 v15, v15, v2, v9
	v_fma_f32 v31, v14, v12, v31
	v_fma_f32 v32, v14, v13, v32
	v_fma_f32 v31, -v15, v13, v31
	v_fma_f32 v32, v15, v12, v32
	ds_write_b32 v6, v31 offset:528
	ds_write_b32 v6, v32 offset:784
	v_mul_f32_e32 v8, v14, v2
	v_mul_f32_e32 v9, v14, v3
	v_fma_f32 v14, -v15, v3, v8
	v_fma_f32 v15, v15, v2, v9
	v_fma_f32 v33, v14, v12, v33
	v_fma_f32 v34, v14, v13, v34
	v_fma_f32 v33, -v15, v13, v33
	v_fma_f32 v34, v15, v12, v34
	ds_write_b32 v6, v33
	ds_write_b32 v6, v34 offset:256
	v_mul_f32_e32 v8, v14, v2
	v_mul_f32_e32 v9, v14, v3
	v_fma_f32 v14, -v15, v3, v8
	v_fma_f32 v15, v15, v2, v9
	v_add_u32_e32 v6, 0xffffef80, v6
	s_sub_i32 s0, s0, 1
	s_cmp_lg_u32 s0, 0
	s_cbranch_scc1 .Lscan_p2_b
; #define LAS __attribute__((address_space(3)))
; template <class Epi, class Sched>
; __device__ __forceinline__ void gemm_phase(PG8_LAS unsigned char* lds, const Gemm g, const Sched& S, const Epi& E) {
;     ...
;     for (int i = 0; i < 2; ++i) { int R, C; stage_rc(tid * 16 + i * 8192, R, C); const int Rb = (R & ~31) + perm32(R & 31);
;         voffA[i] = (unsigned)(R * g.lda + C) * 2u; voffB[i] = (unsigned)(Rb * g.ldb + C) * 2u; }
;     const size_t kstep = (size_t)(BK * 2);
;     const size_t hstepA = (size_t)HALF * g.lda * 2, hstepB = (size_t)HALF * g.ldb * 2;
;     const size_t tstepA = 2 * hstepA, tstepB = 2 * hstepB;
;     const unsigned ldsw = (unsigned)wid * 1024u;
;     const int aoff = lds_byte(wr * 64 + fr, fq * 8), boff = lds_byte(wc * 32 + fr, fq * 8);
;     ...
;     Unit cur, nxt; int ui = 0;
;     if (!S.next(0, cur)) return;
;     f32x4 acc[2][2][4][2];
; #pragma unroll
;     for (int a = 0; a < 2; ++a)
; #pragma unroll
;         for (int b = 0; b < 2; ++b)
; #pragma unroll
;             for (int m = 0; m < 4; ++m)
; #pragma unroll
;                 for (int n = 0; n < 2; ++n) acc[a][b][m][n] = (f32x4){0.f, 0.f, 0.f, 0.f};
;     bf16x8 At[4][2], B0[2][2], B1[2][2];
;     const char* cA = (const char*)g.A + (size_t)cur.pm * tstepA; const char* cB = (const char*)g.Bt + (size_t)cur.pn * tstepB;
;     E.begin(cur, lds, tid);
;     __device__ __forceinline__ void fused(const f32x4 (&acc)[2][2][4][2], const pg8::Unit& u, int wr, int wc, int fr, int fq, LAS unsigned char* lds, int wid, int lane) const {
;     ...
;             asm volatile("s_waitcnt lgkmcnt(0)" ::: "memory"); __builtin_amdgcn_s_barrier(); asm volatile("" ::: "memory");
;             {
;                 const int tid = wid * 64 + lane;
; #pragma unroll
;                 for (int q = 0; q < 8; ++q) { const int e = q * 512 + tid, c = e >> 4, k8 = (e & 15) * 8;
;                     const f32x4 v0 = *(const LAS f32x4*)(T + c * TP + k8), v1 = *(const LAS f32x4*)(T + c * TP + k8 + 4);
;                     v4u w; w.x = cvt_pk_bf16(v0[0], v0[1]); w.y = cvt_pk_bf16(v0[2], v0[3]); w.z = cvt_pk_bf16(v1[0], v1[1]); w.w = cvt_pk_bf16(v1[2], v1[3]);
;                     *(v4u*)(A2 + (row0 + c) * K2 + 512 + bj * 128 + k8) = w; }
;             }
;             asm volatile("s_waitcnt vmcnt(0) lgkmcnt(0)" ::: "memory"); __builtin_amdgcn_s_barrier(); asm volatile("" ::: "memory");
;         }
.Lscan_end_b:
.LBB0_250:
	s_waitcnt lgkmcnt(0)
	s_barrier
	ds_read_b128 v[2:5], v1
	ds_read_b128 v[6:9], v1 offset:16
	s_mov_b32 s0, 0xffffe0
	s_waitcnt lgkmcnt(0)
	v_cvt_pk_bf16_f32 v2, v2, v3
	v_cvt_pk_bf16_f32 v3, v4, v5
	v_cvt_pk_bf16_f32 v4, v6, v7
	v_cvt_pk_bf16_f32 v5, v8, v9
	global_store_dwordx4 v[66:67], v[2:5], off offset:1280
	ds_read_b128 v[2:5], v86
	ds_read_b128 v[6:9], v86 offset:16
	s_waitcnt lgkmcnt(0)
	v_cvt_pk_bf16_f32 v2, v2, v3
	v_cvt_pk_bf16_f32 v3, v4, v5
	v_cvt_pk_bf16_f32 v4, v6, v7
	v_cvt_pk_bf16_f32 v5, v8, v9
	global_store_dwordx4 v[68:69], v[2:5], off offset:1280
	ds_read_b128 v[2:5], v87
	ds_read_b128 v[6:9], v87 offset:16
	s_waitcnt lgkmcnt(0)
	v_cvt_pk_bf16_f32 v2, v2, v3
	v_cvt_pk_bf16_f32 v3, v4, v5
	v_cvt_pk_bf16_f32 v4, v6, v7
	v_cvt_pk_bf16_f32 v5, v8, v9
	global_store_dwordx4 v[70:71], v[2:5], off offset:1280
	ds_read_b128 v[2:5], v88
	ds_read_b128 v[6:9], v88 offset:16
	s_waitcnt lgkmcnt(0)
	v_cvt_pk_bf16_f32 v2, v2, v3
	v_cvt_pk_bf16_f32 v3, v4, v5
	v_cvt_pk_bf16_f32 v4, v6, v7
	v_cvt_pk_bf16_f32 v5, v8, v9
	global_store_dwordx4 v[72:73], v[2:5], off offset:1280
	ds_read_b128 v[2:5], v89
	ds_read_b128 v[6:9], v89 offset:16
	s_waitcnt lgkmcnt(0)
	v_cvt_pk_bf16_f32 v2, v2, v3
	v_cvt_pk_bf16_f32 v3, v4, v5
	v_cvt_pk_bf16_f32 v4, v6, v7
	v_cvt_pk_bf16_f32 v5, v8, v9
	global_store_dwordx4 v[74:75], v[2:5], off offset:1280
	ds_read_b128 v[2:5], v90
	ds_read_b128 v[6:9], v90 offset:16
	s_waitcnt lgkmcnt(0)
	v_cvt_pk_bf16_f32 v2, v2, v3
	v_cvt_pk_bf16_f32 v3, v4, v5
	v_cvt_pk_bf16_f32 v4, v6, v7
	v_cvt_pk_bf16_f32 v5, v8, v9
	global_store_dwordx4 v[76:77], v[2:5], off offset:1280
	ds_read_b128 v[2:5], v91
	ds_read_b128 v[6:9], v91 offset:16
	s_waitcnt lgkmcnt(0)
	v_cvt_pk_bf16_f32 v2, v2, v3
	v_cvt_pk_bf16_f32 v3, v4, v5
	v_cvt_pk_bf16_f32 v4, v6, v7
	v_cvt_pk_bf16_f32 v5, v8, v9
	global_store_dwordx4 v[78:79], v[2:5], off offset:1280
	ds_read_b128 v[2:5], v92
	ds_read_b128 v[6:9], v92 offset:16
	s_waitcnt lgkmcnt(0)
	v_cvt_pk_bf16_f32 v2, v2, v3
	v_cvt_pk_bf16_f32 v3, v4, v5
	v_cvt_pk_bf16_f32 v4, v6, v7
	v_cvt_pk_bf16_f32 v5, v8, v9
	global_store_dwordx4 v[80:81], v[2:5], off offset:1280
	s_waitcnt vmcnt(0) lgkmcnt(0)
	s_barrier
	s_waitcnt vmcnt(0)
	buffer_inv sc1
	v_mov_b32_e32 v2, v244
	s_waitcnt vmcnt(0)
	s_barrier
	s_nop 0
	v_bfe_i32 v4, v2, 27, 1
	v_lshlrev_b32_e32 v1, 4, v2
	v_lshrrev_b32_e32 v4, 22, v4
	v_add_u32_e32 v4, v1, v4
	v_and_b32_e32 v4, 0xfffffc00, v4
	v_sub_u32_e32 v4, v1, v4
	v_ashrrev_i32_e32 v3, 31, v2
	v_lshrrev_b32_e32 v5, 4, v4
	v_lshrrev_b32_e32 v3, 26, v3
	v_bitop3_b32 v6, v5, v4, 32 bitop3:0x6c
	v_add_u32_e32 v3, v2, v3
	v_ashrrev_i32_e32 v5, 31, v6
	v_ashrrev_i32_e32 v3, 6, v3
	v_lshrrev_b32_e32 v5, 26, v5
	v_lshlrev_b32_e32 v4, 3, v3
	v_add_u32_e32 v7, v6, v5
	v_and_b32_e32 v4, -16, v4
	v_ashrrev_i32_e32 v5, 6, v7
	v_and_b32_e32 v7, 0xc0, v7
	v_add_u32_e32 v8, v5, v4
	v_sub_u32_e32 v6, v6, v7
	v_lshlrev_b32_e32 v4, 5, v3
	v_ashrrev_i16_sdwa v6, v248, sext(v6) dst_sel:DWORD dst_unused:UNUSED_PAD src0_sel:DWORD src1_sel:BYTE_0
	v_lshlrev_b32_e32 v9, 1, v8
	v_lshrrev_b32_e32 v10, 2, v8
	v_and_b32_e32 v11, 3, v5
	v_and_b32_e32 v4, 32, v4
	v_bfe_i32 v6, v6, 0, 16
	v_and_b32_e32 v9, 24, v9
	v_and_b32_e32 v10, 4, v10
	v_and_or_b32 v11, v8, s0, v11
	v_add_u32_e32 v7, v4, v6
	v_or3_b32 v9, v11, v10, v9
	v_mul_lo_u32 v8, v8, s35
	v_add_lshl_u32 v130, v7, v8, 1
	v_mul_u32_u24_e32 v8, 0x300, v9
	v_add_u32_e32 v1, 0x2000, v1
	v_add_lshl_u32 v132, v8, v7, 1
	v_ashrrev_i32_e32 v7, 31, v1
	v_lshrrev_b32_e32 v7, 22, v7
	v_add_u32_e32 v7, v1, v7
	v_ashrrev_i32_e32 v7, 10, v7
	v_mul_i32_i24_e32 v8, 0x400, v7
	v_sub_u32_e32 v1, v1, v8
	v_lshrrev_b32_e32 v8, 4, v1
	v_bitop3_b32 v1, v8, v1, 32 bitop3:0x6c
	v_ashrrev_i32_e32 v9, 31, v1
	v_lshrrev_b32_e32 v9, 26, v9
	v_lshlrev_b32_e32 v8, 3, v7
	v_add_u32_e32 v10, v1, v9
	v_and_b32_e32 v8, -16, v8
	v_ashrrev_i32_e32 v9, 6, v10
	v_and_b32_e32 v10, 0xc0, v10
	v_readfirstlane_b32 s4, v2
	v_add_u32_e32 v11, v9, v8
	v_sub_u32_e32 v1, v1, v10
	s_ashr_i32 s5, s4, 6
	v_lshlrev_b32_e32 v8, 5, v7
	v_ashrrev_i16_sdwa v1, v248, sext(v1) dst_sel:DWORD dst_unused:UNUSED_PAD src0_sel:DWORD src1_sel:BYTE_0
	v_lshlrev_b32_e32 v12, 1, v11
	v_lshrrev_b32_e32 v13, 2, v11
	v_and_b32_e32 v14, 3, v9
	v_and_b32_e32 v8, 32, v8
	v_bfe_i32 v10, v1, 0, 16
	v_and_b32_e32 v12, 24, v12
	v_and_b32_e32 v13, 4, v13
	v_and_or_b32 v14, v11, s0, v14
	s_lshl_b32 s59, s5, 10
	v_add_u32_e32 v1, v8, v10
	v_or3_b32 v12, v14, v13, v12
	v_mul_lo_u32 v11, v11, s35
	s_add_i32 s48, s59, 0
	v_add_lshl_u32 v134, v1, v11, 1
	v_mul_u32_u24_e32 v11, 0x300, v12
	s_add_i32 m0, s48, 0x10000
	v_add_lshl_u32 v136, v11, v1, 1
	global_load_lds_dwordx4 v132, s[94:95]
	s_add_i32 m0, s48, 0x12000
	s_add_i32 s49, s48, 0x2000
	global_load_lds_dwordx4 v136, s[94:95]
	s_add_i32 m0, s48, 0x14000
	s_add_i32 s57, s48, 0x4000
	global_load_lds_dwordx4 v132, s[8:9]
	s_add_i32 m0, s48, 0x16000
	s_add_i32 s58, s48, 0x6000
	global_load_lds_dwordx4 v136, s[8:9]
	s_mov_b32 m0, s48
	s_ashr_i32 s6, s4, 8
	global_load_lds_dwordx4 v130, s[52:53]
	s_mov_b32 m0, s49
	s_cmp_eq_u32 s6, 1
	global_load_lds_dwordx4 v134, s[52:53]
	s_mov_b32 m0, s57
	s_cselect_b64 s[0:1], -1, 0
	global_load_lds_dwordx4 v130, s[96:97]
	s_mov_b32 m0, s58
	s_cmp_lg_u32 s6, 1
	global_load_lds_dwordx4 v134, s[96:97]
	s_cbranch_scc1 .LBB0_252
	s_barrier
